# widened scan o-store: permlane16_swap + dwordx4 (4 stores instead of 8), vmcnt counts adjusted
# speedup vs baseline: 1.0972x; 1.0023x over previous
.LBB0_304:
	s_mov_b32 s0, s38
	s_add_i32 s56, s56, 1
	s_add_i32 s38, s38, s39
	s_cmp_lt_u32 s56, s71
	s_cselect_b32 s58, s38, s0
	s_waitcnt vmcnt(4)
	v_mad_i64_i32 v[54:55], s[0:1], s58, v137, v[4:5]
	s_mov_b32 s69, s77
	v_lshl_add_u64 v[56:57], v[54:55], 0, s[76:77]
	v_lshl_add_u64 v[58:59], v[54:55], 0, s[68:69]
	v_lshl_add_u64 v[54:55], v[54:55], 0, s[98:99]
	global_load_dwordx4 v[86:89], v[56:57], off
	global_load_dwordx4 v[82:85], v[58:59], off
	v_lshl_add_u64 v[56:57], v[54:55], 0, s[76:77]
	v_lshl_add_u64 v[54:55], v[54:55], 0, s[68:69]
	global_load_dwordx4 v[78:81], v[56:57], off
	global_load_dwordx4 v[74:77], v[54:55], off
	v_mad_i64_i32 v[54:55], s[0:1], s58, v137, v[112:113]
	v_add_co_u32_e32 v56, vcc, 0x1000, v54
	s_nop 1
	v_addc_co_u32_e32 v57, vcc, 0, v55, vcc
	global_load_dwordx4 v[66:69], v[54:55], off
	global_load_dwordx4 v[58:61], v[54:55], off offset:128
	global_load_dwordx4 v[70:73], v[56:57], off offset:2112
	global_load_dwordx4 v[62:65], v[56:57], off offset:2240
	v_mad_i64_i32 v[54:55], s[0:1], s58, v137, v[114:115]
	global_load_dwordx4 v[54:57], v[54:55], off
	s_and_b64 vcc, exec, s[4:5]
	s_cbranch_vccnz .LBB0_314
	v_add3_u32 v98, v107, v186, 16
	v_add3_u32 v99, v107, v187, 16
	v_add3_u32 v100, v107, v190, 16
	v_add3_u32 v101, v107, v191, 16
	v_add3_u32 v102, v107, v194, 16
	v_add3_u32 v103, v107, v195, 16
	v_add3_u32 v104, v107, v198, 16
	v_add3_u32 v105, v107, v199, 16
	ds_read2st64_b32 v[220:221], v165 offset1:1
	ds_read2st64_b32 v[222:223], v165 offset0:2 offset1:3
	ds_read_u16 v236, v98
	ds_read_u16 v237, v98 offset:8192
	ds_read_u16 v238, v98 offset:128
	ds_read_u16 v239, v98 offset:8320
	ds_read_u16 v240, v99 offset:256
	ds_read_u16 v241, v99 offset:8448
	ds_read_u16 v242, v99 offset:384
	ds_read_u16 v243, v99 offset:8576
	s_waitcnt lgkmcnt(0)
	ds_read2st64_b32 v[224:225], v188 offset1:1
	ds_read2st64_b32 v[226:227], v188 offset0:2 offset1:3
	ds_read_u16 v244, v100
	ds_read_u16 v245, v100 offset:8192
	ds_read_u16 v246, v100 offset:128
	ds_read_u16 v247, v100 offset:8320
	ds_read_u16 v248, v101 offset:256
	ds_read_u16 v249, v101 offset:8448
	ds_read_u16 v250, v101 offset:384
	ds_read_u16 v251, v101 offset:8576
	v_add_f32_e32 v2, v220, v221
	v_add_f32_e32 v2, v2, v222
	v_add_f32_e32 v253, v2, v223
	v_mul_f32_e32 v223, 0x3fb8aa3b, v253
	v_exp_f32_e32 v223, v223
	v_cndmask_b32_e64 v2, 0, v220, s[18:19]
	v_cndmask_b32_e64 v220, 0, v221, s[14:15]
	v_add_f32_e32 v2, v2, v220
	v_cndmask_b32_e64 v220, 0, v222, s[20:21]
	v_add_f32_e32 v2, v2, v220
	v_add_f32_e32 v220, v95, v2
	v_sub_f32_e32 v221, v253, v220
	v_add_f32_e32 v2, v91, v220
	v_cndmask_b32_e64 v95, v221, v2, s[2:3]
	v_sub_f32_e32 v2, v221, v91
	v_add_f32_e32 v253, v94, v220
	v_cndmask_b32_e64 v91, v2, v253, s[2:3]
	v_sub_f32_e32 v2, v221, v94
	v_add_f32_e32 v253, v93, v220
	v_cndmask_b32_e64 v94, v2, v253, s[2:3]
	v_sub_f32_e32 v2, v221, v93
	v_add_f32_e32 v253, v92, v220
	v_cndmask_b32_e64 v93, v2, v253, s[2:3]
	v_mul_f32_e32 v95, 0x3fb8aa3b, v95
	v_mul_f32_e32 v91, 0x3fb8aa3b, v91
	v_mul_f32_e32 v94, 0x3fb8aa3b, v94
	v_mul_f32_e32 v93, 0x3fb8aa3b, v93
	v_exp_f32_e32 v95, v95
	v_exp_f32_e32 v91, v91
	v_exp_f32_e32 v94, v94
	v_exp_f32_e32 v93, v93
	v_rcp_f32_e32 v92, v95
	v_rcp_f32_e32 v220, v91
	v_rcp_f32_e32 v221, v94
	v_rcp_f32_e32 v222, v93
	s_waitcnt lgkmcnt(0)
	s_and_saveexec_b64 s[0:1], s[82:83]
	ds_write_b32 v185, v223
	s_or_b64 exec, exec, s[0:1]
	v_lshlrev_b32_e32 v2, 16, v236
	v_lshlrev_b32_e32 v253, 16, v237
	v_mul_f32_e32 v2, v95, v2
	v_mul_f32_e32 v253, v92, v253
	v_cvt_pk_bf16_f32 v236, v2, v253
	ds_write_b16 v98, v236
	ds_write_b16_d16_hi v98, v236 offset:8192
	v_mul_f32_e32 v95, v223, v253
	v_lshlrev_b32_e32 v2, 16, v238
	v_lshlrev_b32_e32 v253, 16, v239
	v_mul_f32_e32 v2, v91, v2
	v_mul_f32_e32 v253, v220, v253
	v_cvt_pk_bf16_f32 v238, v2, v253
	ds_write_b16 v98, v238 offset:128
	ds_write_b16_d16_hi v98, v238 offset:8320
	v_mul_f32_e32 v91, v223, v253
	v_lshlrev_b32_e32 v2, 16, v240
	v_lshlrev_b32_e32 v253, 16, v241
	v_mul_f32_e32 v2, v94, v2
	v_mul_f32_e32 v253, v221, v253
	v_cvt_pk_bf16_f32 v240, v2, v253
	ds_write_b16 v99, v240 offset:256
	ds_write_b16_d16_hi v99, v240 offset:8448
	v_mul_f32_e32 v94, v223, v253
	v_lshlrev_b32_e32 v2, 16, v242
	v_lshlrev_b32_e32 v253, 16, v243
	v_mul_f32_e32 v2, v93, v2
	v_mul_f32_e32 v253, v222, v253
	v_cvt_pk_bf16_f32 v242, v2, v253
	ds_write_b16 v99, v242 offset:384
	ds_write_b16_d16_hi v99, v242 offset:8576
	v_mul_f32_e32 v93, v223, v253
	v_cvt_pk_bf16_f32 v236, v95, v91
	v_cvt_pk_bf16_f32 v237, v94, v93
	v_add_u32_e32 v252, v182, v144
	ds_write_b64 v252, v[236:237] offset:16384
	s_waitcnt lgkmcnt(5)
	ds_read2st64_b32 v[228:229], v192 offset1:1
	ds_read2st64_b32 v[230:231], v192 offset0:2 offset1:3
	ds_read_u16 v236, v102
	ds_read_u16 v237, v102 offset:8192
	ds_read_u16 v238, v102 offset:128
	ds_read_u16 v239, v102 offset:8320
	ds_read_u16 v240, v103 offset:256
	ds_read_u16 v241, v103 offset:8448
	ds_read_u16 v242, v103 offset:384
	ds_read_u16 v243, v103 offset:8576
	v_add_f32_e32 v2, v224, v225
	v_add_f32_e32 v2, v2, v226
	v_add_f32_e32 v253, v2, v227
	v_mul_f32_e32 v227, 0x3fb8aa3b, v253
	v_exp_f32_e32 v227, v227
	v_cndmask_b32_e64 v2, 0, v224, s[18:19]
	v_cndmask_b32_e64 v224, 0, v225, s[14:15]
	v_add_f32_e32 v2, v2, v224
	v_cndmask_b32_e64 v224, 0, v226, s[20:21]
	v_add_f32_e32 v2, v2, v224
	v_add_f32_e32 v224, v211, v2
	v_sub_f32_e32 v225, v253, v224
	v_add_f32_e32 v2, v90, v224
	v_cndmask_b32_e64 v211, v225, v2, s[2:3]
	v_sub_f32_e32 v2, v225, v90
	v_add_f32_e32 v253, v210, v224
	v_cndmask_b32_e64 v90, v2, v253, s[2:3]
	v_sub_f32_e32 v2, v225, v210
	v_add_f32_e32 v253, v135, v224
	v_cndmask_b32_e64 v210, v2, v253, s[2:3]
	v_sub_f32_e32 v2, v225, v135
	v_add_f32_e32 v253, v209, v224
	v_cndmask_b32_e64 v135, v2, v253, s[2:3]
	v_mul_f32_e32 v211, 0x3fb8aa3b, v211
	v_mul_f32_e32 v90, 0x3fb8aa3b, v90
	v_mul_f32_e32 v210, 0x3fb8aa3b, v210
	v_mul_f32_e32 v135, 0x3fb8aa3b, v135
	v_exp_f32_e32 v211, v211
	v_exp_f32_e32 v90, v90
	v_exp_f32_e32 v210, v210
	v_exp_f32_e32 v135, v135
	v_rcp_f32_e32 v209, v211
	v_rcp_f32_e32 v224, v90
	v_rcp_f32_e32 v225, v210
	v_rcp_f32_e32 v226, v135
	s_waitcnt lgkmcnt(0)
	s_and_saveexec_b64 s[0:1], s[82:83]
	ds_write_b32 v189, v227
	s_or_b64 exec, exec, s[0:1]
	v_lshlrev_b32_e32 v2, 16, v244
	v_lshlrev_b32_e32 v253, 16, v245
	v_mul_f32_e32 v2, v211, v2
	v_mul_f32_e32 v253, v209, v253
	v_cvt_pk_bf16_f32 v244, v2, v253
	ds_write_b16 v100, v244
	ds_write_b16_d16_hi v100, v244 offset:8192
	v_mul_f32_e32 v211, v227, v253
	v_lshlrev_b32_e32 v2, 16, v246
	v_lshlrev_b32_e32 v253, 16, v247
	v_mul_f32_e32 v2, v90, v2
	v_mul_f32_e32 v253, v224, v253
	v_cvt_pk_bf16_f32 v246, v2, v253
	ds_write_b16 v100, v246 offset:128
	ds_write_b16_d16_hi v100, v246 offset:8320
	v_mul_f32_e32 v90, v227, v253
	v_lshlrev_b32_e32 v2, 16, v248
	v_lshlrev_b32_e32 v253, 16, v249
	v_mul_f32_e32 v2, v210, v2
	v_mul_f32_e32 v253, v225, v253
	v_cvt_pk_bf16_f32 v248, v2, v253
	ds_write_b16 v101, v248 offset:256
	ds_write_b16_d16_hi v101, v248 offset:8448
	v_mul_f32_e32 v210, v227, v253
	v_lshlrev_b32_e32 v2, 16, v250
	v_lshlrev_b32_e32 v253, 16, v251
	v_mul_f32_e32 v2, v135, v2
	v_mul_f32_e32 v253, v226, v253
	v_cvt_pk_bf16_f32 v250, v2, v253
	ds_write_b16 v101, v250 offset:384
	ds_write_b16_d16_hi v101, v250 offset:8576
	v_mul_f32_e32 v135, v227, v253
	v_cvt_pk_bf16_f32 v244, v211, v90
	v_cvt_pk_bf16_f32 v245, v210, v135
	ds_write_b64 v203, v[244:245] offset:16384
	s_waitcnt lgkmcnt(5)
	ds_read2st64_b32 v[232:233], v196 offset1:1
	ds_read2st64_b32 v[234:235], v196 offset0:2 offset1:3
	ds_read_u16 v244, v104
	ds_read_u16 v245, v104 offset:8192
	ds_read_u16 v246, v104 offset:128
	ds_read_u16 v247, v104 offset:8320
	ds_read_u16 v248, v105 offset:256
	ds_read_u16 v249, v105 offset:8448
	ds_read_u16 v250, v105 offset:384
	ds_read_u16 v251, v105 offset:8576
	v_add_f32_e32 v2, v228, v229
	v_add_f32_e32 v2, v2, v230
	v_add_f32_e32 v253, v2, v231
	v_mul_f32_e32 v231, 0x3fb8aa3b, v253
	v_exp_f32_e32 v231, v231
	v_cndmask_b32_e64 v2, 0, v228, s[18:19]
	v_cndmask_b32_e64 v228, 0, v229, s[14:15]
	v_add_f32_e32 v2, v2, v228
	v_cndmask_b32_e64 v228, 0, v230, s[20:21]
	v_add_f32_e32 v2, v2, v228
	v_add_f32_e32 v228, v215, v2
	v_sub_f32_e32 v229, v253, v228
	v_add_f32_e32 v2, v97, v228
	v_cndmask_b32_e64 v215, v229, v2, s[2:3]
	v_sub_f32_e32 v2, v229, v97
	v_add_f32_e32 v253, v214, v228
	v_cndmask_b32_e64 v97, v2, v253, s[2:3]
	v_sub_f32_e32 v2, v229, v214
	v_add_f32_e32 v253, v212, v228
	v_cndmask_b32_e64 v214, v2, v253, s[2:3]
	v_sub_f32_e32 v2, v229, v212
	v_add_f32_e32 v253, v213, v228
	v_cndmask_b32_e64 v212, v2, v253, s[2:3]
	v_mul_f32_e32 v215, 0x3fb8aa3b, v215
	v_mul_f32_e32 v97, 0x3fb8aa3b, v97
	v_mul_f32_e32 v214, 0x3fb8aa3b, v214
	v_mul_f32_e32 v212, 0x3fb8aa3b, v212
	v_exp_f32_e32 v215, v215
	v_exp_f32_e32 v97, v97
	v_exp_f32_e32 v214, v214
	v_exp_f32_e32 v212, v212
	v_rcp_f32_e32 v213, v215
	v_rcp_f32_e32 v228, v97
	v_rcp_f32_e32 v229, v214
	v_rcp_f32_e32 v230, v212
	s_waitcnt lgkmcnt(0)
	s_and_saveexec_b64 s[0:1], s[82:83]
	ds_write_b32 v193, v231
	s_or_b64 exec, exec, s[0:1]
	v_lshlrev_b32_e32 v2, 16, v236
	v_lshlrev_b32_e32 v253, 16, v237
	v_mul_f32_e32 v2, v215, v2
	v_mul_f32_e32 v253, v213, v253
	v_cvt_pk_bf16_f32 v236, v2, v253
	ds_write_b16 v102, v236
	ds_write_b16_d16_hi v102, v236 offset:8192
	v_mul_f32_e32 v215, v231, v253
	v_lshlrev_b32_e32 v2, 16, v238
	v_lshlrev_b32_e32 v253, 16, v239
	v_mul_f32_e32 v2, v97, v2
	v_mul_f32_e32 v253, v228, v253
	v_cvt_pk_bf16_f32 v238, v2, v253
	ds_write_b16 v102, v238 offset:128
	ds_write_b16_d16_hi v102, v238 offset:8320
	v_mul_f32_e32 v97, v231, v253
	v_lshlrev_b32_e32 v2, 16, v240
	v_lshlrev_b32_e32 v253, 16, v241
	v_mul_f32_e32 v2, v214, v2
	v_mul_f32_e32 v253, v229, v253
	v_cvt_pk_bf16_f32 v240, v2, v253
	ds_write_b16 v103, v240 offset:256
	ds_write_b16_d16_hi v103, v240 offset:8448
	v_mul_f32_e32 v214, v231, v253
	v_lshlrev_b32_e32 v2, 16, v242
	v_lshlrev_b32_e32 v253, 16, v243
	v_mul_f32_e32 v2, v212, v2
	v_mul_f32_e32 v253, v230, v253
	v_cvt_pk_bf16_f32 v242, v2, v253
	ds_write_b16 v103, v242 offset:384
	ds_write_b16_d16_hi v103, v242 offset:8576
	v_mul_f32_e32 v212, v231, v253
	v_cvt_pk_bf16_f32 v236, v215, v97
	v_cvt_pk_bf16_f32 v237, v214, v212
	ds_write_b64 v204, v[236:237] offset:16384
	v_add_f32_e32 v2, v232, v233
	v_add_f32_e32 v2, v2, v234
	v_add_f32_e32 v253, v2, v235
	v_mul_f32_e32 v235, 0x3fb8aa3b, v253
	v_exp_f32_e32 v235, v235
	v_cndmask_b32_e64 v2, 0, v232, s[18:19]
	v_cndmask_b32_e64 v232, 0, v233, s[14:15]
	v_add_f32_e32 v2, v2, v232
	v_cndmask_b32_e64 v232, 0, v234, s[20:21]
	v_add_f32_e32 v2, v2, v232
	v_add_f32_e32 v232, v219, v2
	v_sub_f32_e32 v233, v253, v232
	v_add_f32_e32 v2, v96, v232
	v_cndmask_b32_e64 v219, v233, v2, s[2:3]
	v_sub_f32_e32 v2, v233, v96
	v_add_f32_e32 v253, v218, v232
	v_cndmask_b32_e64 v96, v2, v253, s[2:3]
	v_sub_f32_e32 v2, v233, v218
	v_add_f32_e32 v253, v216, v232
	v_cndmask_b32_e64 v218, v2, v253, s[2:3]
	v_sub_f32_e32 v2, v233, v216
	v_add_f32_e32 v253, v217, v232
	v_cndmask_b32_e64 v216, v2, v253, s[2:3]
	v_mul_f32_e32 v219, 0x3fb8aa3b, v219
	v_mul_f32_e32 v96, 0x3fb8aa3b, v96
	v_mul_f32_e32 v218, 0x3fb8aa3b, v218
	v_mul_f32_e32 v216, 0x3fb8aa3b, v216
	v_exp_f32_e32 v219, v219
	v_exp_f32_e32 v96, v96
	v_exp_f32_e32 v218, v218
	v_exp_f32_e32 v216, v216
	v_rcp_f32_e32 v217, v219
	v_rcp_f32_e32 v232, v96
	v_rcp_f32_e32 v233, v218
	v_rcp_f32_e32 v234, v216
	s_waitcnt lgkmcnt(0)
	s_and_saveexec_b64 s[0:1], s[82:83]
	ds_write_b32 v197, v235
	s_or_b64 exec, exec, s[0:1]
	v_lshlrev_b32_e32 v2, 16, v244
	v_lshlrev_b32_e32 v253, 16, v245
	v_mul_f32_e32 v2, v219, v2
	v_mul_f32_e32 v253, v217, v253
	v_cvt_pk_bf16_f32 v244, v2, v253
	ds_write_b16 v104, v244
	ds_write_b16_d16_hi v104, v244 offset:8192
	v_mul_f32_e32 v219, v235, v253
	v_lshlrev_b32_e32 v2, 16, v246
	v_lshlrev_b32_e32 v253, 16, v247
	v_mul_f32_e32 v2, v96, v2
	v_mul_f32_e32 v253, v232, v253
	v_cvt_pk_bf16_f32 v246, v2, v253
	ds_write_b16 v104, v246 offset:128
	ds_write_b16_d16_hi v104, v246 offset:8320
	v_mul_f32_e32 v96, v235, v253
	v_lshlrev_b32_e32 v2, 16, v248
	v_lshlrev_b32_e32 v253, 16, v249
	v_mul_f32_e32 v2, v218, v2
	v_mul_f32_e32 v253, v233, v253
	v_cvt_pk_bf16_f32 v248, v2, v253
	ds_write_b16 v105, v248 offset:256
	ds_write_b16_d16_hi v105, v248 offset:8448
	v_mul_f32_e32 v218, v235, v253
	v_lshlrev_b32_e32 v2, 16, v250
	v_lshlrev_b32_e32 v253, 16, v251
	v_mul_f32_e32 v2, v216, v2
	v_mul_f32_e32 v253, v234, v253
	v_cvt_pk_bf16_f32 v250, v2, v253
	ds_write_b16 v105, v250 offset:384
	ds_write_b16_d16_hi v105, v250 offset:8576
	v_mul_f32_e32 v216, v235, v253
	v_cvt_pk_bf16_f32 v244, v219, v96
	v_cvt_pk_bf16_f32 v245, v218, v216
	ds_write_b64 v205, v[244:245] offset:16384
	s_waitcnt lgkmcnt(0)
	s_barrier

.LBB0_330:
	s_andn2_saveexec_b64 s[0:1], s[0:1]
	s_or_b64 exec, exec, s[0:1]
	v_cvt_pk_bf16_f32 v90, v90, v91
	v_cvt_pk_bf16_f32 v91, v92, v93
	v_add_u32_e32 v92, v210, v154
	v_add_u32_e32 v94, v202, v200
	ds_write_b64 v92, v[90:91] offset:40960
	s_waitcnt lgkmcnt(0)
	s_barrier
	ds_read_b128 v[102:105], v94 offset:24576
	v_add_u32_e32 v95, v202, v201
	ds_read_b128 v[90:93], v95 offset:24576
	ds_read_b128 v[98:101], v94 offset:26624
	ds_read_b128 v[94:97], v95 offset:26624
	ds_read_b128 v[210:213], v209 offset:40960
	ds_read_b128 v[218:221], v209 offset:43008
	ds_read_b128 v[242:245], v2 offset:40960
	s_waitcnt lgkmcnt(2)
	v_mfma_f32_16x16x32_bf16 v[214:217], v[102:105], v[210:213], 0
	ds_read_b128 v[226:229], v209 offset:45056
	ds_read_b128 v[234:237], v209 offset:47104
	v_ashrrev_i32_e32 v135, 31, v134
	v_mfma_f32_16x16x32_bf16 v[210:213], v[98:101], v[210:213], 0
	s_mov_b64 s[0:1], -1
	s_and_b64 vcc, exec, s[4:5]
	s_waitcnt lgkmcnt(2)
	v_mfma_f32_16x16x32_bf16 v[214:217], v[90:93], v[242:245], v[214:217]
	v_mfma_f32_16x16x32_bf16 v[210:213], v[94:97], v[242:245], v[210:213]
	ds_read_b128 v[242:245], v2 offset:43008
	v_mfma_f32_16x16x32_bf16 v[222:225], v[102:105], v[218:221], 0
	v_mfma_f32_16x16x32_bf16 v[218:221], v[98:101], v[218:221], 0
	s_waitcnt lgkmcnt(0)
	v_mfma_f32_16x16x32_bf16 v[222:225], v[90:93], v[242:245], v[222:225]
	v_mfma_f32_16x16x32_bf16 v[218:221], v[94:97], v[242:245], v[218:221]
	ds_read_b128 v[242:245], v2 offset:45056
	v_mfma_f32_16x16x32_bf16 v[230:233], v[102:105], v[226:229], 0
	v_mfma_f32_16x16x32_bf16 v[226:229], v[98:101], v[226:229], 0
	s_waitcnt lgkmcnt(0)
	v_mfma_f32_16x16x32_bf16 v[230:233], v[90:93], v[242:245], v[230:233]
	v_mfma_f32_16x16x32_bf16 v[226:229], v[94:97], v[242:245], v[226:229]
	ds_read_b128 v[242:245], v2 offset:47104
	v_mfma_f32_16x16x32_bf16 v[238:241], v[102:105], v[234:237], 0
	v_mfma_f32_16x16x32_bf16 v[234:237], v[98:101], v[234:237], 0
	s_waitcnt lgkmcnt(0)
	v_mfma_f32_16x16x32_bf16 v[238:241], v[90:93], v[242:245], v[238:241]
	v_mfma_f32_16x16x32_bf16 v[234:237], v[94:97], v[242:245], v[234:237]
	ds_read_b128 v[242:245], v206 offset:49152
	ds_read_b128 v[246:249], v206 offset:51200
	ds_read_b128 v[250:253], v209
	s_waitcnt lgkmcnt(0)
	v_mfma_f32_16x16x32_bf16 v[214:217], v[242:245], v[250:253], v[214:217]
	v_mfma_f32_16x16x32_bf16 v[210:213], v[246:249], v[250:253], v[210:213]
	ds_read_b128 v[250:253], v209 offset:2048
	s_waitcnt lgkmcnt(0)
	v_mfma_f32_16x16x32_bf16 v[222:225], v[242:245], v[250:253], v[222:225]
	v_mfma_f32_16x16x32_bf16 v[218:221], v[246:249], v[250:253], v[218:221]
	ds_read_b128 v[250:253], v209 offset:4096
	s_waitcnt lgkmcnt(0)
	v_mfma_f32_16x16x32_bf16 v[230:233], v[242:245], v[250:253], v[230:233]
	v_mfma_f32_16x16x32_bf16 v[226:229], v[246:249], v[250:253], v[226:229]
	ds_read_b128 v[250:253], v209 offset:6144
	s_waitcnt lgkmcnt(0)
	v_mfma_f32_16x16x32_bf16 v[238:241], v[242:245], v[250:253], v[238:241]
	v_mfma_f32_16x16x32_bf16 v[234:237], v[246:249], v[250:253], v[234:237]
	ds_read_b128 v[242:245], v207 offset:49152
	ds_read_b128 v[246:249], v207 offset:51200
	ds_read_b128 v[250:253], v2
	s_waitcnt lgkmcnt(0)
	v_mfma_f32_16x16x32_bf16 v[214:217], v[242:245], v[250:253], v[214:217]
	v_mfma_f32_16x16x32_bf16 v[210:213], v[246:249], v[250:253], v[210:213]
	ds_read_b128 v[250:253], v2 offset:2048
	s_waitcnt lgkmcnt(0)
	v_mfma_f32_16x16x32_bf16 v[222:225], v[242:245], v[250:253], v[222:225]
	v_mfma_f32_16x16x32_bf16 v[218:221], v[246:249], v[250:253], v[218:221]
	ds_read_b128 v[250:253], v2 offset:4096
	s_waitcnt lgkmcnt(0)
	v_mfma_f32_16x16x32_bf16 v[230:233], v[242:245], v[250:253], v[230:233]
	v_mfma_f32_16x16x32_bf16 v[226:229], v[246:249], v[250:253], v[226:229]
	ds_read_b128 v[250:253], v2 offset:6144
	s_waitcnt lgkmcnt(0)
	v_mfma_f32_16x16x32_bf16 v[238:241], v[242:245], v[250:253], v[238:241]
	v_mfma_f32_16x16x32_bf16 v[234:237], v[246:249], v[250:253], v[234:237]
	v_mbcnt_lo_u32_b32 v242, -1, 0
	v_mbcnt_hi_u32_b32 v242, -1, v242
	v_bfe_u32 v242, v242, 4, 1
	v_mul_u32_u24_e32 v242, 24, v242
	v_mov_b32_e32 v243, 0
	v_cvt_pk_bf16_f32 v244, v214, v215
	v_cvt_pk_bf16_f32 v245, v216, v217
	v_cvt_pk_bf16_f32 v246, v210, v211
	v_cvt_pk_bf16_f32 v247, v212, v213
	v_cvt_pk_bf16_f32 v248, v222, v223
	v_cvt_pk_bf16_f32 v249, v224, v225
	v_cvt_pk_bf16_f32 v250, v218, v219
	v_cvt_pk_bf16_f32 v251, v220, v221
	v_cvt_pk_bf16_f32 v212, v230, v231
	v_cvt_pk_bf16_f32 v213, v232, v233
	v_cvt_pk_bf16_f32 v214, v226, v227
	v_cvt_pk_bf16_f32 v215, v228, v229
	v_lshl_add_u64 v[252:253], v[132:133], 0, v[242:243]
	v_subrev_u32_e32 v220, 48, v134
	v_ashrrev_i32_e32 v221, 31, v220
	v_lshlrev_b64 v[220:221], 11, v[220:221]
	v_lshl_add_u64 v[220:221], v[252:253], 0, v[220:221]
	v_subrev_u32_e32 v222, 32, v134
	v_ashrrev_i32_e32 v223, 31, v222
	v_lshlrev_b64 v[222:223], 11, v[222:223]
	v_lshl_add_u64 v[222:223], v[252:253], 0, v[222:223]
	v_add_u32_e32 v224, -16, v134
	v_ashrrev_i32_e32 v225, 31, v224
	v_lshlrev_b64 v[224:225], 11, v[224:225]
	v_lshl_add_u64 v[224:225], v[252:253], 0, v[224:225]
	v_lshlrev_b64 v[226:227], 11, v[134:135]
	v_lshl_add_u64 v[226:227], v[252:253], 0, v[226:227]
	v_cvt_pk_bf16_f32 v216, v238, v239
	v_cvt_pk_bf16_f32 v217, v240, v241
	v_cvt_pk_bf16_f32 v218, v234, v235
	v_cvt_pk_bf16_f32 v219, v236, v237
	v_permlane16_swap_b32_e32 v244, v246
	v_permlane16_swap_b32_e32 v245, v247
	global_store_dwordx4 v[220:221], v[244:247], off
	v_permlane16_swap_b32_e32 v248, v250
	v_permlane16_swap_b32_e32 v249, v251
	global_store_dwordx4 v[222:223], v[248:251], off
	v_permlane16_swap_b32_e32 v212, v214
	v_permlane16_swap_b32_e32 v213, v215
	global_store_dwordx4 v[224:225], v[212:215], off
	v_permlane16_swap_b32_e32 v216, v218
	v_permlane16_swap_b32_e32 v217, v219
	global_store_dwordx4 v[226:227], v[216:219], off
	s_nop 3
	ds_read_b128 v[218:221], v208
	ds_read_b128 v[222:225], v208 offset:64
	ds_read_b128 v[226:229], v208 offset:128
	ds_read_b128 v[230:233], v208 offset:192
	ds_read_b128 v[234:237], v209 offset:16384
	ds_read_b128 v[238:241], v209 offset:18432
	ds_read_b128 v[242:245], v209 offset:20480
	ds_read_b128 v[246:249], v209 offset:22528
	ds_read_b128 v[250:253], v2 offset:16384
	s_waitcnt lgkmcnt(8)
	v_pk_mul_f32 v[22:23], v[22:23], v[218:219]
	v_pk_mul_f32 v[24:25], v[24:25], v[220:221]
	v_pk_mul_f32 v[26:27], v[26:27], v[218:219]
	v_pk_mul_f32 v[28:29], v[28:29], v[220:221]
	s_waitcnt lgkmcnt(7)
	v_pk_mul_f32 v[30:31], v[30:31], v[222:223]
	v_pk_mul_f32 v[32:33], v[32:33], v[224:225]
	v_pk_mul_f32 v[34:35], v[34:35], v[222:223]
	v_pk_mul_f32 v[36:37], v[36:37], v[224:225]
	s_waitcnt lgkmcnt(6)
	v_pk_mul_f32 v[38:39], v[38:39], v[226:227]
	v_pk_mul_f32 v[40:41], v[40:41], v[228:229]
	v_pk_mul_f32 v[42:43], v[42:43], v[226:227]
	v_pk_mul_f32 v[44:45], v[44:45], v[228:229]
	s_waitcnt lgkmcnt(5)
	v_pk_mul_f32 v[46:47], v[46:47], v[230:231]
	v_pk_mul_f32 v[48:49], v[48:49], v[232:233]
	v_pk_mul_f32 v[50:51], v[50:51], v[230:231]
	v_pk_mul_f32 v[52:53], v[52:53], v[232:233]
	ds_read_b128 v[218:221], v2 offset:18432
	ds_read_b128 v[222:225], v2 offset:20480
	ds_read_b128 v[226:229], v2 offset:22528
	s_waitcnt lgkmcnt(7)
	v_mfma_f32_16x16x32_bf16 v[22:25], v[234:237], v[102:105], v[22:25]
	v_mfma_f32_16x16x32_bf16 v[26:29], v[234:237], v[98:101], v[26:29]
	s_waitcnt lgkmcnt(6)
	v_mfma_f32_16x16x32_bf16 v[30:33], v[238:241], v[102:105], v[30:33]
	v_mfma_f32_16x16x32_bf16 v[34:37], v[238:241], v[98:101], v[34:37]
	s_waitcnt lgkmcnt(5)
	v_mfma_f32_16x16x32_bf16 v[38:41], v[242:245], v[102:105], v[38:41]
	v_mfma_f32_16x16x32_bf16 v[42:45], v[242:245], v[98:101], v[42:45]
	s_waitcnt lgkmcnt(4)
	v_mfma_f32_16x16x32_bf16 v[46:49], v[246:249], v[102:105], v[46:49]
	v_mfma_f32_16x16x32_bf16 v[50:53], v[246:249], v[98:101], v[50:53]
	s_waitcnt lgkmcnt(3)
	v_mfma_f32_16x16x32_bf16 v[22:25], v[250:253], v[90:93], v[22:25]
	v_mfma_f32_16x16x32_bf16 v[26:29], v[250:253], v[94:97], v[26:29]
	s_waitcnt lgkmcnt(2)
	v_mfma_f32_16x16x32_bf16 v[30:33], v[218:221], v[90:93], v[30:33]
	v_mfma_f32_16x16x32_bf16 v[34:37], v[218:221], v[94:97], v[34:37]
	s_waitcnt lgkmcnt(1)
	v_mfma_f32_16x16x32_bf16 v[38:41], v[222:225], v[90:93], v[38:41]
	v_mfma_f32_16x16x32_bf16 v[42:45], v[222:225], v[94:97], v[42:45]
	s_waitcnt lgkmcnt(0)
	v_mfma_f32_16x16x32_bf16 v[46:49], v[226:229], v[90:93], v[46:49]
	v_mfma_f32_16x16x32_bf16 v[50:53], v[226:229], v[94:97], v[50:53]
	s_nop 1
	v_cvt_pk_bf16_f32 v90, v22, v23
	v_cvt_pk_bf16_f32 v91, v24, v25
	v_cvt_pk_bf16_f32 v92, v26, v27
	v_cvt_pk_bf16_f32 v93, v28, v29
	ds_write2st64_b64 v146, v[90:91], v[92:93] offset0:96 offset1:100
	v_cvt_pk_bf16_f32 v90, v30, v31
	v_cvt_pk_bf16_f32 v91, v32, v33
	v_cvt_pk_bf16_f32 v92, v34, v35
	v_cvt_pk_bf16_f32 v93, v36, v37
	ds_write2st64_b64 v149, v[90:91], v[92:93] offset0:96 offset1:100
	v_cvt_pk_bf16_f32 v90, v38, v39
	v_cvt_pk_bf16_f32 v91, v40, v41
	v_cvt_pk_bf16_f32 v92, v42, v43
	v_cvt_pk_bf16_f32 v93, v44, v45
	ds_write2st64_b64 v152, v[90:91], v[92:93] offset0:96 offset1:100
	v_cvt_pk_bf16_f32 v90, v46, v47
	v_cvt_pk_bf16_f32 v91, v48, v49
	v_cvt_pk_bf16_f32 v92, v50, v51
	v_cvt_pk_bf16_f32 v93, v52, v53
	ds_write2st64_b64 v155, v[90:91], v[92:93] offset0:96 offset1:100
	s_waitcnt lgkmcnt(0)
	s_barrier
	s_cbranch_vccnz .LBB0_332
	s_mov_b64 s[0:1], 0
	s_waitcnt vmcnt(12)
	ds_write_b128 v156, v[86:89]
	s_waitcnt vmcnt(11)
	ds_write_b128 v156, v[82:85] offset:8192
	s_waitcnt vmcnt(10)
	ds_write_b128 v156, v[78:81] offset:4096
	s_waitcnt vmcnt(9)
	ds_write_b128 v156, v[74:77] offset:12288
.LBB0_332:
	s_andn2_b64 vcc, exec, s[0:1]
	s_cbranch_vccnz .LBB0_334
	s_waitcnt vmcnt(12)
	v_lshlrev_b32_e32 v90, 16, v86
	v_and_b32_e32 v91, 0xffff0000, v86
	s_waitcnt vmcnt(11)
	v_lshlrev_b32_e32 v92, 16, v82
	v_and_b32_e32 v93, 0xffff0000, v82
	v_pk_mul_f32 v[90:91], v[120:121], v[90:91]
	s_nop 0
	v_cvt_pk_bf16_f32 v82, v90, v91
	v_pk_mul_f32 v[90:91], v[124:125], v[92:93]
	s_nop 0
	v_cvt_pk_bf16_f32 v86, v90, v91
	v_pk_mul_f32 v[90:91], v[128:129], v[92:93]
	v_lshlrev_b32_e32 v92, 16, v83
	v_cvt_pk_bf16_f32 v2, v90, v91
	v_lshlrev_b32_e32 v90, 16, v87
	v_and_b32_e32 v91, 0xffff0000, v87
	v_and_b32_e32 v93, 0xffff0000, v83
	v_pk_mul_f32 v[90:91], v[120:121], v[90:91]
	ds_write_b16 v157, v2 offset:16384
	ds_write_b16_d16_hi v157, v2 offset:16512
	v_cvt_pk_bf16_f32 v83, v90, v91
	v_pk_mul_f32 v[90:91], v[124:125], v[92:93]
	s_nop 0
	v_cvt_pk_bf16_f32 v87, v90, v91
	v_pk_mul_f32 v[90:91], v[128:129], v[92:93]
	v_lshlrev_b32_e32 v92, 16, v84
	v_cvt_pk_bf16_f32 v2, v90, v91
	v_lshlrev_b32_e32 v90, 16, v88
	v_and_b32_e32 v91, 0xffff0000, v88
	v_and_b32_e32 v93, 0xffff0000, v84
	v_pk_mul_f32 v[90:91], v[120:121], v[90:91]
	ds_write_b16 v158, v2 offset:16640
	ds_write_b16_d16_hi v158, v2 offset:16768
	v_cvt_pk_bf16_f32 v84, v90, v91
	v_pk_mul_f32 v[90:91], v[124:125], v[92:93]
	s_nop 0
	v_cvt_pk_bf16_f32 v88, v90, v91
	v_pk_mul_f32 v[90:91], v[128:129], v[92:93]
	v_lshlrev_b32_e32 v92, 16, v85
	v_cvt_pk_bf16_f32 v2, v90, v91
	v_lshlrev_b32_e32 v90, 16, v89
	v_and_b32_e32 v91, 0xffff0000, v89
	v_and_b32_e32 v93, 0xffff0000, v85
	v_pk_mul_f32 v[90:91], v[120:121], v[90:91]
	ds_write_b16 v159, v2 offset:16896
	ds_write_b16_d16_hi v159, v2 offset:17024
	v_cvt_pk_bf16_f32 v85, v90, v91
	v_pk_mul_f32 v[90:91], v[124:125], v[92:93]
	s_nop 0
	v_cvt_pk_bf16_f32 v89, v90, v91
	v_pk_mul_f32 v[90:91], v[128:129], v[92:93]
	s_nop 0
	v_cvt_pk_bf16_f32 v2, v90, v91
	ds_write_b16 v160, v2 offset:17152
	ds_write_b16_d16_hi v160, v2 offset:17280
	ds_write_b128 v156, v[82:85]
	ds_write_b128 v156, v[86:89] offset:8192
	s_waitcnt vmcnt(10)
	v_lshlrev_b32_e32 v82, 16, v78
	v_and_b32_e32 v83, 0xffff0000, v78
	s_waitcnt vmcnt(9)
	v_lshlrev_b32_e32 v84, 16, v74
	v_and_b32_e32 v85, 0xffff0000, v74
	v_pk_mul_f32 v[82:83], v[122:123], v[82:83]
	s_nop 0
	v_cvt_pk_bf16_f32 v74, v82, v83
	v_pk_mul_f32 v[82:83], v[126:127], v[84:85]
	s_nop 0
	v_cvt_pk_bf16_f32 v78, v82, v83
	v_pk_mul_f32 v[82:83], v[130:131], v[84:85]
	v_lshlrev_b32_e32 v84, 16, v75
	v_cvt_pk_bf16_f32 v2, v82, v83
	v_lshlrev_b32_e32 v82, 16, v79
	v_and_b32_e32 v83, 0xffff0000, v79
	v_and_b32_e32 v85, 0xffff0000, v75
	v_pk_mul_f32 v[82:83], v[122:123], v[82:83]
	ds_write_b16 v161, v2 offset:16384
	ds_write_b16_d16_hi v161, v2 offset:16512
	v_cvt_pk_bf16_f32 v75, v82, v83
	v_pk_mul_f32 v[82:83], v[126:127], v[84:85]
	s_nop 0
	v_cvt_pk_bf16_f32 v79, v82, v83
	v_pk_mul_f32 v[82:83], v[130:131], v[84:85]
	v_lshlrev_b32_e32 v84, 16, v76
	v_cvt_pk_bf16_f32 v2, v82, v83
	v_lshlrev_b32_e32 v82, 16, v80
	v_and_b32_e32 v83, 0xffff0000, v80
	v_and_b32_e32 v85, 0xffff0000, v76
	v_pk_mul_f32 v[82:83], v[122:123], v[82:83]
	ds_write_b16 v162, v2 offset:16640
	ds_write_b16_d16_hi v162, v2 offset:16768
	v_cvt_pk_bf16_f32 v76, v82, v83
	v_pk_mul_f32 v[82:83], v[126:127], v[84:85]
	s_nop 0
	v_cvt_pk_bf16_f32 v80, v82, v83
	v_pk_mul_f32 v[82:83], v[130:131], v[84:85]
	v_lshlrev_b32_e32 v84, 16, v77
	v_cvt_pk_bf16_f32 v2, v82, v83
	v_lshlrev_b32_e32 v82, 16, v81
	v_and_b32_e32 v83, 0xffff0000, v81
	v_and_b32_e32 v85, 0xffff0000, v77
	v_pk_mul_f32 v[82:83], v[122:123], v[82:83]
	ds_write_b16 v163, v2 offset:16896
	ds_write_b16_d16_hi v163, v2 offset:17024
	v_cvt_pk_bf16_f32 v77, v82, v83
	v_pk_mul_f32 v[82:83], v[126:127], v[84:85]
	s_nop 0
	v_cvt_pk_bf16_f32 v81, v82, v83
	v_pk_mul_f32 v[82:83], v[130:131], v[84:85]
	s_nop 0
	v_cvt_pk_bf16_f32 v2, v82, v83
	ds_write_b16 v164, v2 offset:17152
	ds_write_b16_d16_hi v164, v2 offset:17280
	ds_write_b128 v156, v[74:77] offset:4096
	ds_write_b128 v156, v[78:81] offset:12288
.LBB0_334:
	s_waitcnt vmcnt(6)
	v_perm_b32 v2, v70, v66, s33
	v_perm_b32 v66, v70, v66, s72
	ds_write2_b32 v168, v2, v66 offset1:32
	v_perm_b32 v2, v71, v67, s33
	ds_write_b32 v169, v2 offset:24576
	v_perm_b32 v2, v71, v67, s72
	ds_write_b32 v170, v2 offset:24576
	v_perm_b32 v2, v72, v68, s33
	ds_write_b32 v171, v2 offset:24576
	v_perm_b32 v2, v72, v68, s72
	ds_write_b32 v172, v2 offset:24576
	v_perm_b32 v2, v73, v69, s33
	ds_write_b32 v173, v2 offset:24576
	v_perm_b32 v2, v73, v69, s72
	ds_write_b32 v174, v2 offset:24576
	s_waitcnt vmcnt(5)
	v_perm_b32 v2, v62, v58, s33
	v_perm_b32 v58, v62, v58, s72
	ds_write2_b32 v175, v2, v58 offset1:32
	v_perm_b32 v2, v63, v59, s33
	ds_write_b32 v176, v2 offset:24576
	v_perm_b32 v2, v63, v59, s72
	ds_write_b32 v177, v2 offset:24576
	v_perm_b32 v2, v64, v60, s33
	ds_write_b32 v178, v2 offset:24576
	v_perm_b32 v2, v64, v60, s72
	ds_write_b32 v179, v2 offset:24576
	v_perm_b32 v2, v65, v61, s33
	ds_write_b32 v180, v2 offset:24576
	v_perm_b32 v2, v65, v61, s72
	s_and_b64 vcc, exec, s[4:5]
	v_mov_b64_e32 v[90:91], v[108:109]
	v_mov_b64_e32 v[96:97], v[108:109]
	v_mov_b64_e32 v[94:95], v[116:117]
	v_mov_b64_e32 v[92:93], v[118:119]
	v_mov_b32_e32 v211, v117
	v_mov_b32_e32 v215, v117
	v_mov_b32_e32 v219, v117
	v_mov_b32_e32 v210, v116
	v_mov_b32_e32 v135, v119
	v_mov_b32_e32 v209, v118
	v_mov_b32_e32 v214, v116
	v_mov_b32_e32 v212, v119
	v_mov_b32_e32 v213, v118
	v_mov_b32_e32 v218, v116
	v_mov_b32_e32 v216, v119
	v_mov_b32_e32 v217, v118
	ds_write_b32 v181, v2 offset:24576
	s_cbranch_vccnz .LBB0_303
	s_waitcnt vmcnt(4)
	v_cndmask_b32_e64 v57, 0, v57, s[10:11]
	v_cndmask_b32_e64 v56, 0, v56, s[10:11]
	v_cndmask_b32_e64 v55, 0, v55, s[10:11]
	v_cndmask_b32_e64 v54, 0, v54, s[10:11]
	s_nop 1
	v_mfma_f32_16x16x32_bf16 v[58:61], v[54:57], v[6:9], 0
	v_mfma_f32_16x16x32_bf16 v[62:65], v[54:57], v[10:13], 0
	s_nop 6
	v_add_f32_e32 v2, v111, v58
	v_min_f32_e32 v67, 0, v2
	v_mul_f32_e64 v2, |v2|, s73
	v_exp_f32_e32 v2, v2
	s_nop 0
	v_add_f32_e32 v2, 1.0, v2
	v_log_f32_e32 v2, v2
	s_nop 0
	v_mul_f32_e32 v58, 0x3f317217, v2
	v_fma_f32 v58, v2, s67, -v58
	v_fmac_f32_e32 v58, 0x3377d1cf, v2
	v_fmac_f32_e32 v58, 0x3f317217, v2
	v_mov_b32_e32 v2, v58
	v_mov_b32_e32 v58, 0
	v_sub_f32_e32 v69, v2, v58
	v_add_f32_e32 v2, v111, v59
	v_min_f32_e32 v58, 0, v2
	v_mul_f32_e64 v2, |v2|, s73
	v_exp_f32_e32 v2, v2
	s_nop 0
	v_add_f32_e32 v2, 1.0, v2
	v_log_f32_e32 v2, v2
	s_nop 0
	v_mul_f32_e32 v59, 0x3f317217, v2
	v_fma_f32 v59, v2, s67, -v59
	v_fmac_f32_e32 v59, 0x3377d1cf, v2
	v_fmac_f32_e32 v59, 0x3f317217, v2
	v_mov_b32_e32 v2, v59
	v_mov_b32_e32 v59, 0
	v_sub_f32_e32 v2, v2, v59
	v_sub_f32_e32 v70, v58, v2
	v_add_f32_e32 v2, v111, v60
	v_min_f32_e32 v58, 0, v2
	v_mul_f32_e64 v2, |v2|, s73
	v_exp_f32_e32 v2, v2
	s_nop 0
	v_add_f32_e32 v2, 1.0, v2
	v_log_f32_e32 v2, v2
	s_nop 0
	v_mul_f32_e32 v59, 0x3f317217, v2
	v_fma_f32 v59, v2, s67, -v59
	v_fmac_f32_e32 v59, 0x3377d1cf, v2
	v_fmac_f32_e32 v59, 0x3f317217, v2
	v_mov_b32_e32 v2, v59
	v_mov_b32_e32 v59, 0
	v_sub_f32_e32 v2, v2, v59
	v_sub_f32_e32 v71, v58, v2
	v_add_f32_e32 v2, v111, v61
	v_min_f32_e32 v58, 0, v2
	v_mul_f32_e64 v2, |v2|, s73
	v_exp_f32_e32 v2, v2
	s_nop 0
	v_add_f32_e32 v2, 1.0, v2
	v_log_f32_e32 v2, v2
	s_nop 0
	v_mul_f32_e32 v59, 0x3f317217, v2
	v_fma_f32 v59, v2, s67, -v59
	v_fmac_f32_e32 v59, 0x3377d1cf, v2
	v_fmac_f32_e32 v59, 0x3f317217, v2
	v_mov_b32_e32 v2, v59
	v_mov_b32_e32 v59, 0
	v_sub_f32_e32 v2, v2, v59
	v_sub_f32_e32 v72, v58, v2
	v_add_f32_e32 v2, v139, v62
	v_min_f32_e32 v66, 0, v2
	v_mul_f32_e64 v2, |v2|, s73
	v_exp_f32_e32 v2, v2
	v_and_b32_e32 v62, 64, v1
	v_add_f32_e32 v2, 1.0, v2
	v_log_f32_e32 v2, v2
	s_nop 0
	v_mul_f32_e32 v58, 0x3f317217, v2
	v_fma_f32 v58, v2, s67, -v58
	v_fmac_f32_e32 v58, 0x3377d1cf, v2
	v_fmac_f32_e32 v58, 0x3f317217, v2
	v_mov_b32_e32 v2, v58
	v_mov_b32_e32 v58, 0
	v_sub_f32_e32 v68, v2, v58
	v_add_u32_e32 v2, -16, v1
	v_pk_add_f32 v[58:59], v[66:67], v[68:69] neg_lo:[0,1] neg_hi:[0,1]
	v_cmp_lt_i32_e32 vcc, v2, v62
	v_subrev_u32_e32 v66, 32, v1
	v_pk_mul_f32 v[90:91], v[58:59], s[96:97] op_sel_hi:[1,0]
	v_cndmask_b32_e32 v2, v2, v1, vcc
	v_cmp_lt_i32_e32 vcc, v66, v62
	v_fmamk_f32 v94, v70, 0x3d800000, v91
	v_fmamk_f32 v93, v71, 0x3d800000, v94
	v_cndmask_b32_e32 v66, v66, v1, vcc
	v_lshlrev_b32_e32 v67, 2, v66
	v_subrev_u32_e32 v66, 48, v1
	v_cmp_lt_i32_e32 vcc, v66, v62
	v_lshlrev_b32_e32 v2, 2, v2
	v_or_b32_e32 v62, v62, v166
	v_cndmask_b32_e32 v66, v66, v1, vcc
	v_fmamk_f32 v92, v72, 0x3d800000, v93
	v_lshlrev_b32_e32 v68, 2, v66
	v_lshlrev_b32_e32 v66, 2, v62
	ds_bpermute_b32 v62, v2, v92
	ds_bpermute_b32 v69, v67, v92
	ds_bpermute_b32 v70, v68, v92
	v_mfma_f32_16x16x32_bf16 v[58:61], v[54:57], v[14:17], 0
	s_waitcnt lgkmcnt(2)
	v_cndmask_b32_e64 v62, v62, 0, s[6:7]
	s_waitcnt lgkmcnt(1)
	v_cndmask_b32_e64 v69, 0, v69, s[12:13]
	v_add_f32_e32 v62, v62, v69
	s_waitcnt lgkmcnt(0)
	v_cndmask_b32_e64 v69, 0, v70, s[8:9]
	v_add_f32_e32 v95, v62, v69
	v_add_f32_e32 v62, v95, v92
	ds_bpermute_b32 v62, v66, v62
	v_mfma_f32_16x16x32_bf16 v[54:57], v[54:57], v[18:21], 0
	s_and_saveexec_b64 s[0:1], s[6:7]
	s_cbranch_execz .LBB0_337
	s_waitcnt lgkmcnt(0)
	ds_write_b32 v167, v62
